# m7_attn_order_swap_odd_wgs
# speedup vs baseline: 1.0025x; 1.0025x over previous
; #define LAS __attribute__((address_space(3)))
; __global__ void __launch_bounds__(512, 2) fwd_kernel(Args a0) {
;     extern __shared__ __attribute__((aligned(16))) unsigned char lds_raw[];
;     LAS unsigned char* lds = (LAS unsigned char*)lds_raw;
;     const int G = gridDim.x, bx = blockIdx.x;
;     const int vcu = (G % 8 == 0) ? (bx % 8) * (G / 8) + bx / 8 : bx;
;     const int ph_lo = a0.ph_lo, ph_hi = a0.ph_hi;
_Z10fwd_kernel4Args:
	s_mov_b64 s[60:61], s[0:1]
	v_writelane_b32 v252, 0, 20
	s_load_dword s3, s[0:1], 0xb0
	s_nop 0
	s_load_dwordx2 s[0:1], s[0:1], 0xa0
	s_add_u32 s4, s60, 0xb0
	s_addc_u32 s5, s61, 0
	s_mov_b32 s96, s2
	v_writelane_b32 v253, s4, 0
	s_waitcnt lgkmcnt(0)
	s_and_b32 s2, s3, 7
	s_cmp_lg_u32 s2, 0
	v_writelane_b32 v253, s5, 1
	v_writelane_b32 v253, s96, 2
	s_cbranch_scc1 .LBB0_2
	s_ashr_i32 s4, s96, 31
	s_lshr_b32 s4, s4, 29
	s_add_i32 s4, s96, s4
	s_and_b32 s5, s4, -8
	s_ashr_i32 s2, s3, 3
	s_sub_i32 s5, s96, s5
	s_mul_i32 s2, s2, s5
	s_ashr_i32 s4, s4, 3
	s_add_i32 s2, s2, s4
	v_writelane_b32 v253, s2, 2

; #define LAS __attribute__((address_space(3)))
; __device__ __forceinline__ int tid_opaque() { int t = threadIdx.x; asm volatile("" : "+v"(t)); return t; }
; __device__ __forceinline__ void attn_phase(LAS unsigned char* lds, const Args& a, int layer, int vcu, int G) {
;     const bf16_t* proj = (const bf16_t*)(a.ws + WS_PROJ); bf16_t* mix = (bf16_t*)(a.ws + WS_MIX);
;     const int lane = tid_opaque() & 63;
;     const float a1 = wave_sum(a.in[8][layer * 64 + lane] * a.in[9][layer * 64 + lane]);
;     const float a2 = wave_sum(a.in[10][layer * 64 + lane] * a.in[11][layer * 64 + lane]);
;     const float lam_init = layer ? 0.35550906759096927f : 0.2f;
;     const float lam = __expf(a1) - __expf(a2) + lam_init;
;     const float post = 1.0f - lam_init;
;     for (int u = vcu; u < BATCH * 4 * (SEQ / 128); u += G) { const int bh = u >> 5, qblk = u & 31;
;         attn_unit<1>(lds, proj, mix, bh >> 2, qblk, bh & 3, nullptr, a.in[12] + layer * 128, lam, post); }
;     for (int u = vcu; u < BATCH * 4 * (SEQ / 128); u += G) { const int b = u >> 7, rem = u & 127, qblk = rem >> 2, hj = rem & 3;
;         attn_unit<0>(lds, proj, mix, b, qblk, hj, a.in[7] + layer * 8, nullptr, 0.f, 0.f); }
.Lsw_setup:
	v_readlane_b32 s0, v252, 20
	s_cmp_lg_u32 s0, 0
	s_cbranch_scc1 .Lsw_noinit
	v_readlane_b32 s0, v253, 2
	s_and_b32 s0, s0, 1
	s_min_u32 s0, s0, 1
	v_writelane_b32 v252, s0, 20
	s_nop 1
.Lsw_noinit:
	v_readlane_b32 s0, v254, 62
	v_mov_b32_e32 v0, v228
	v_readlane_b32 s1, v254, 63
	s_load_dwordx8 s[48:55], s[0:1], 0x40
	v_readlane_b32 s2, v252, 2
	s_lshl_b32 s0, s2, 6
	s_waitcnt vmcnt(4)
	v_and_or_b32 v2, v0, 63, s0
	v_ashrrev_i32_e32 v3, 31, v2
	v_lshlrev_b64 v[2:3], 2, v[2:3]
	s_waitcnt lgkmcnt(0)
	v_lshl_add_u64 v[4:5], s[48:49], 0, v[2:3]
	global_load_dword v0, v[4:5], off
	v_lshl_add_u64 v[4:5], s[50:51], 0, v[2:3]
	global_load_dword v6, v[4:5], off
	v_lshl_add_u64 v[4:5], s[52:53], 0, v[2:3]
	v_lshl_add_u64 v[2:3], s[54:55], 0, v[2:3]
	global_load_dword v4, v[4:5], off
	v_xor_b32_e32 v5, 1, v232
	global_load_dword v2, v[2:3], off
	v_and_b32_e32 v3, 64, v232
	v_add_u32_e32 v3, 64, v3
	v_cmp_lt_i32_e32 vcc, v5, v3
	v_xor_b32_e32 v7, 2, v232
	v_xor_b32_e32 v8, 4, v232
	v_cndmask_b32_e32 v5, v232, v5, vcc
	v_lshlrev_b32_e32 v5, 2, v5
	v_cmp_lt_i32_e32 vcc, v7, v3
	v_xor_b32_e32 v9, 8, v232
	v_xor_b32_e32 v10, 16, v232
	v_cndmask_b32_e32 v7, v232, v7, vcc
	v_lshlrev_b32_e32 v7, 2, v7
	v_cmp_lt_i32_e32 vcc, v8, v3
	v_xor_b32_e32 v11, 32, v232
	v_readlane_b32 s0, v253, 14
	v_readlane_b32 s1, v253, 15
	s_waitcnt vmcnt(2)
	v_mul_f32_e32 v12, v0, v6
	ds_bpermute_b32 v12, v5, v12
	s_waitcnt vmcnt(0)
	v_mul_f32_e32 v13, v4, v2
	ds_bpermute_b32 v5, v5, v13
	s_waitcnt lgkmcnt(1)
	v_fmac_f32_e32 v12, v0, v6
	ds_bpermute_b32 v0, v7, v12
	s_waitcnt lgkmcnt(1)
	v_fmac_f32_e32 v5, v4, v2
	ds_bpermute_b32 v2, v7, v5
	v_cndmask_b32_e32 v4, v232, v8, vcc
	v_lshlrev_b32_e32 v4, 2, v4
	s_waitcnt lgkmcnt(1)
	v_add_f32_e32 v0, v12, v0
	v_cmp_lt_i32_e32 vcc, v9, v3
	s_waitcnt lgkmcnt(0)
	v_add_f32_e32 v2, v5, v2
	ds_bpermute_b32 v5, v4, v0
	ds_bpermute_b32 v4, v4, v2
	v_cndmask_b32_e32 v6, v232, v9, vcc
	v_lshlrev_b32_e32 v6, 2, v6
	v_cmp_lt_i32_e32 vcc, v10, v3
	s_waitcnt lgkmcnt(1)
	v_add_f32_e32 v0, v0, v5
	s_waitcnt lgkmcnt(0)
	v_add_f32_e32 v2, v2, v4
	ds_bpermute_b32 v4, v6, v0
	ds_bpermute_b32 v5, v6, v2
	v_cndmask_b32_e32 v6, v232, v10, vcc
	v_lshlrev_b32_e32 v6, 2, v6
	v_cmp_lt_i32_e32 vcc, v11, v3
	s_waitcnt lgkmcnt(1)
	v_add_f32_e32 v0, v0, v4
	s_waitcnt lgkmcnt(0)
	v_add_f32_e32 v4, v2, v5
	ds_bpermute_b32 v2, v6, v0
	ds_bpermute_b32 v5, v6, v4
	v_cndmask_b32_e32 v3, v232, v11, vcc
	v_lshlrev_b32_e32 v159, 2, v3
	s_andn2_b64 vcc, exec, s[0:1]
	s_waitcnt lgkmcnt(1)
	v_add_f32_e32 v2, v0, v2
	s_waitcnt lgkmcnt(0)
	v_add_f32_e32 v0, v4, v5
	ds_bpermute_b32 v4, v159, v2
	ds_bpermute_b32 v3, v159, v0
	s_cbranch_vccnz .LBB0_264
	s_waitcnt lgkmcnt(1)
	v_add_f32_e32 v2, v2, v4
	s_waitcnt lgkmcnt(0)
	v_add_f32_e32 v0, v0, v3
	v_readlane_b32 s40, v254, 62
	v_mul_f32_e32 v2, 0x3fb8aa3b, v2
	v_mul_f32_e32 v0, 0x3fb8aa3b, v0
	v_readlane_b32 s41, v254, 63
	s_add_i32 s0, s76, 5
	v_exp_f32_e32 v2, v2
	v_exp_f32_e32 v0, v0
	s_load_dwordx2 s[40:41], s[40:41], 0x60
	s_cmp_lt_u32 s0, 13
	s_cselect_b64 vcc, -1, 0
	s_lshl_b32 s0, s2, 7
	s_ashr_i32 s1, s0, 31
	v_cndmask_b32_e32 v5, v233, v234, vcc
	v_sub_f32_e32 v0, v2, v0
	s_lshl_b64 s[0:1], s[0:1], 2
	v_add_f32_e32 v154, v5, v0
	s_waitcnt lgkmcnt(0)
	s_add_u32 s40, s40, s0
	v_readlane_b32 s51, v253, 2
	v_sub_f32_e32 v165, 1.0, v5
	s_addc_u32 s41, s41, s1
	v_mov_b32_e32 v155, v154
	s_mov_b32 s50, s51
	v_readlane_b32 s0, v252, 20
	s_cmp_eq_u32 s0, 1
	s_cbranch_scc1 .LBB0_246
	s_branch .LBB0_172
.LBB0_171:
	s_waitcnt lgkmcnt(0)
	s_barrier
	s_add_i32 s51, s51, s3
	s_add_i32 s50, s50, s3
	s_cmpk_gt_i32 s51, 0x1ff
	s_cbranch_scc0 .LBB0_172
	v_readlane_b32 s0, v252, 20
	s_cmp_eq_u32 s0, 2
	s_cbranch_scc1 .LBB0_264
	s_branch .LBB0_246

; __device__ __forceinline__ unsigned cvtpk(float lo, float hi) { f32x2_t v = {lo, hi}; bf16x2_t b = __builtin_convertvector(v, bf16x2_t); return __builtin_bit_cast(unsigned, b); }
; template <int MODE>
; __device__ __forceinline__ void attn_unit(LAS unsigned char* lds, const bf16_t* __restrict__ proj, bf16_t* __restrict__ mix, int b, int qblk, int hj,
;                                           const float* __restrict__ sink, const float* __restrict__ subln, float lam, float post) {
;     ...
;     __syncthreads();
;     const float lt = l + __shfl_xor(l, 32);
;     const float inv = 1.0f / lt;
;     bf16_t* op = mix + (rowbase + qpos) * DM + ocol + 4 * hi;
;     if (MODE == 0) {
; #pragma unroll
;         for (int e = 0; e < NEB; ++e)
; #pragma unroll
;             for (int g4 = 0; g4 < 4; ++g4)
;                 *(u32x2*)(op + 32 * e + 8 * g4) = (u32x2){cvtpk(O[e][4 * g4] * inv, O[e][4 * g4 + 1] * inv), cvtpk(O[e][4 * g4 + 2] * inv, O[e][4 * g4 + 3] * inv)};
; __device__ __forceinline__ void attn_phase(LAS unsigned char* lds, const Args& a, int layer, int vcu, int G) {
;     ...
;     for (int u = vcu; u < BATCH * 4 * (SEQ / 128); u += G) { const int bh = u >> 5, qblk = u & 31;
;         attn_unit<1>(lds, proj, mix, bh >> 2, qblk, bh & 3, nullptr, a.in[12] + layer * 128, lam, post); }
;     for (int u = vcu; u < BATCH * 4 * (SEQ / 128); u += G) { const int b = u >> 7, rem = u & 127, qblk = rem >> 2, hj = rem & 3;
;         attn_unit<0>(lds, proj, mix, b, qblk, hj, a.in[7] + layer * 8, nullptr, 0.f, 0.f); }
.LBB0_248:
	ds_bpermute_b32 v0, v159, v109
	s_waitcnt vmcnt(0) lgkmcnt(0)
	s_barrier
	s_add_i32 s9, s9, s3
	v_add_f32_e32 v0, v109, v0
	v_div_scale_f32 v34, s[44:45], v0, v0, 1.0
	v_rcp_f32_e32 v35, v34
	v_div_scale_f32 v36, vcc, 1.0, v0, 1.0
	v_readlane_b32 s44, v252, 5
	v_fma_f32 v37, -v34, v35, 1.0
	v_fmac_f32_e32 v35, v37, v35
	v_mul_f32_e32 v37, v36, v35
	v_fma_f32 v38, -v34, v37, v36
	v_fmac_f32_e32 v37, v38, v35
	v_fma_f32 v34, -v34, v37, v36
	v_div_fmas_f32 v34, v34, v35, v37
	v_lshlrev_b64 v[36:37], 11, v[98:99]
	v_readlane_b32 s45, v252, 6
	v_div_fixup_f32 v34, v34, v0, 1.0
	v_lshlrev_b32_e32 v0, 1, v101
	v_lshl_add_u64 v[36:37], s[44:45], 0, v[36:37]
	v_lshl_add_u64 v[36:37], s[42:43], 1, v[36:37]
	v_pk_mul_f32 v[2:3], v[2:3], v[34:35] op_sel_hi:[1,0]
	v_pk_mul_f32 v[4:5], v[4:5], v[34:35] op_sel_hi:[1,0]
	v_lshl_add_u64 v[36:37], v[36:37], 0, v[0:1]
	v_cvt_pk_bf16_f32 v2, v2, v3
	v_cvt_pk_bf16_f32 v3, v4, v5
	global_store_dwordx2 v[36:37], v[2:3], off
	v_pk_mul_f32 v[2:3], v[6:7], v[34:35] op_sel_hi:[1,0]
	v_pk_mul_f32 v[4:5], v[8:9], v[34:35] op_sel_hi:[1,0]
	v_cvt_pk_bf16_f32 v2, v2, v3
	v_cvt_pk_bf16_f32 v3, v4, v5
	global_store_dwordx2 v[36:37], v[2:3], off offset:16
	v_pk_mul_f32 v[2:3], v[10:11], v[34:35] op_sel_hi:[1,0]
	v_pk_mul_f32 v[4:5], v[12:13], v[34:35] op_sel_hi:[1,0]
	v_cvt_pk_bf16_f32 v2, v2, v3
	v_cvt_pk_bf16_f32 v3, v4, v5
	global_store_dwordx2 v[36:37], v[2:3], off offset:32
	v_pk_mul_f32 v[2:3], v[14:15], v[34:35] op_sel_hi:[1,0]
	v_pk_mul_f32 v[4:5], v[16:17], v[34:35] op_sel_hi:[1,0]
	v_cvt_pk_bf16_f32 v2, v2, v3
	v_cvt_pk_bf16_f32 v3, v4, v5
	global_store_dwordx2 v[36:37], v[2:3], off offset:48
	v_pk_mul_f32 v[2:3], v[18:19], v[34:35] op_sel_hi:[1,0]
	v_pk_mul_f32 v[4:5], v[20:21], v[34:35] op_sel_hi:[1,0]
	v_cvt_pk_bf16_f32 v2, v2, v3
	v_cvt_pk_bf16_f32 v3, v4, v5
	global_store_dwordx2 v[36:37], v[2:3], off offset:64
	v_pk_mul_f32 v[2:3], v[22:23], v[34:35] op_sel_hi:[1,0]
	v_pk_mul_f32 v[4:5], v[24:25], v[34:35] op_sel_hi:[1,0]
	v_cvt_pk_bf16_f32 v2, v2, v3
	v_cvt_pk_bf16_f32 v3, v4, v5
	global_store_dwordx2 v[36:37], v[2:3], off offset:80
	v_pk_mul_f32 v[2:3], v[26:27], v[34:35] op_sel_hi:[1,0]
	v_pk_mul_f32 v[4:5], v[28:29], v[34:35] op_sel_hi:[1,0]
	v_cvt_pk_bf16_f32 v2, v2, v3
	v_cvt_pk_bf16_f32 v3, v4, v5
	global_store_dwordx2 v[36:37], v[2:3], off offset:96
	v_pk_mul_f32 v[2:3], v[30:31], v[34:35] op_sel_hi:[1,0]
	v_pk_mul_f32 v[4:5], v[32:33], v[34:35] op_sel_hi:[1,0]
	v_cvt_pk_bf16_f32 v2, v2, v3
	v_cvt_pk_bf16_f32 v3, v4, v5
	global_store_dwordx2 v[36:37], v[2:3], off offset:112
	s_waitcnt lgkmcnt(0)
	s_barrier
	s_cmpk_gt_i32 s9, 0x1ff
	s_cbranch_scc0 .LBB0_249
	v_readlane_b32 s0, v252, 20
	s_cmp_eq_u32 s0, 1
	s_cbranch_scc0 .LBB0_264
	s_mov_b32 s0, 2
	v_writelane_b32 v252, s0, 20
	s_nop 1
	s_branch .Lsw_setup

; __device__ __forceinline__ void attn_phase(LAS unsigned char* lds, const Args& a, int layer, int vcu, int G) {
;     ...
;     for (int u = vcu; u < BATCH * 4 * (SEQ / 128); u += G) { const int bh = u >> 5, qblk = u & 31;
;         attn_unit<1>(lds, proj, mix, bh >> 2, qblk, bh & 3, nullptr, a.in[12] + layer * 128, lam, post); }
;     for (int u = vcu; u < BATCH * 4 * (SEQ / 128); u += G) { const int b = u >> 7, rem = u & 127, qblk = rem >> 2, hj = rem & 3;
;         attn_unit<0>(lds, proj, mix, b, qblk, hj, a.in[7] + layer * 8, nullptr, 0.f, 0.f); }
; }
.LBB0_264:
	s_mov_b64 s[0:1], 0
	v_writelane_b32 v252, s0, 20
	s_nop 1
	v_writelane_b32 v252, s0, 10
	s_nop 1
	v_writelane_b32 v252, s1, 11
